# GEMM2b sub-pass order depends on WG parity (odd: C,B,A; even: A,B,C)
# speedup vs baseline: 1.0020x; 1.0020x over previous
; __global__ void __launch_bounds__(NWAVES * 64, 2) hybrid_fwd(Args A) {
;     ...
;             else if ((s == 2 && EN(3)) || (s == 3 && EN(4)) || (s == 4 && EN(5))) {
;                 const bool split = C.G >= 192; bool go = (s == 4); int k0 = split ? KSPLIT : 0, kl = D - k0, gg = C.G, cc = C.bid, mrows = M; size_t roff = 0;
;                 if (s == 2) { go = phase_mixers(A, C, l, rep ? DUP_UN : 7); k0 = 0; kl = KSPLIT; gg = C.G - 128; cc = C.bid - 128; mrows = MP; }
;                 if (s == 3) { phase_post(A, C, l, split ? 8 : 0); go = split && C.bid < 8 && !rep; k0 = 0; kl = KSPLIT; gg = 8; cc = C.bid; mrows = MS; roff = (size_t)MP * D; }
;                 if (go) { pg8::Gemm g{WS_PTR(const bf16, WS_XN) + roff + k0, WS_PTR(const bf16, WS_WOUTT) + (size_t)l * D * D + k0, mrows, D, kl, D}; pg8::StaticOrder S; S.init(mrows, D, gg, cc);
;                     const bool first = (l == 0) && (s != 4 || !split);
;                     float* Hout = ((rep && s == 4) ? WS_PTR(float, WS_U) : A.out) + roff;
;                     pg8::EpiResN E{Hout, first ? (s == 3 ? A.in[I_XS] : A.in[I_XP]) : Hout, first ? A.in[I_XS] - (size_t)MP * D : Hout, WS_PTR(bf16, WS_HB), WS_PTR(float, WS_SS) + (size_t)(l + 1) * M, s == 4 && !rep};
;                     pg8::gemm_phase<pg8::EpiResN, pg8::StaticOrder, G2_ALIGN, true>(C.lds, g, S, E); }
.LBB0_675:
	s_mov_b32 s98, -1
	v_writelane_b32 v255, s98, 61
	s_mov_b32 s98, 0
	v_writelane_b32 v255, s98, 62
	v_writelane_b32 v255, s98, 63
	v_readlane_b32 s98, v255, 53
	s_cmp_eq_u32 s98, 4
	s_cbranch_scc1 .Lmy_g2_next
	s_movk_i32 s11, 0x81
	v_readlane_b32 s30, v253, 0
	v_readlane_b32 s17, v253, 3
	v_readlane_b32 s3, v253, 19
	v_readlane_b32 s8, v253, 18
	s_branch .LBB0_1183

; __global__ void __launch_bounds__(NWAVES * 64, 2) hybrid_fwd(Args A) {
;     ...
;             else if ((s == 2 && EN(3)) || (s == 3 && EN(4)) || (s == 4 && EN(5))) {
;                 const bool split = C.G >= 192; bool go = (s == 4); int k0 = split ? KSPLIT : 0, kl = D - k0, gg = C.G, cc = C.bid, mrows = M; size_t roff = 0;
;                 if (s == 2) { go = phase_mixers(A, C, l, rep ? DUP_UN : 7); k0 = 0; kl = KSPLIT; gg = C.G - 128; cc = C.bid - 128; mrows = MP; }
;                 if (s == 3) { phase_post(A, C, l, split ? 8 : 0); go = split && C.bid < 8 && !rep; k0 = 0; kl = KSPLIT; gg = 8; cc = C.bid; mrows = MS; roff = (size_t)MP * D; }
;                 if (go) { pg8::Gemm g{WS_PTR(const bf16, WS_XN) + roff + k0, WS_PTR(const bf16, WS_WOUTT) + (size_t)l * D * D + k0, mrows, D, kl, D}; pg8::StaticOrder S; S.init(mrows, D, gg, cc);
;                     const bool first = (l == 0) && (s != 4 || !split);
;                     float* Hout = ((rep && s == 4) ? WS_PTR(float, WS_U) : A.out) + roff;
;                     pg8::EpiResN E{Hout, first ? (s == 3 ? A.in[I_XS] : A.in[I_XP]) : Hout, first ? A.in[I_XS] - (size_t)MP * D : Hout, WS_PTR(bf16, WS_HB), WS_PTR(float, WS_SS) + (size_t)(l + 1) * M, s == 4 && !rep};
;                     pg8::gemm_phase<pg8::EpiResN, pg8::StaticOrder, G2_ALIGN, true>(C.lds, g, S, E); }
.Lmy_g2_next:
	v_readlane_b32 s0, v255, 61
	s_add_i32 s0, s0, 1
	v_writelane_b32 v255, s0, 61
	s_cmp_gt_u32 s0, 2
	s_cbranch_scc1 .Lmy_g2_done
	v_readlane_b32 s1, v253, 0
	s_sub_i32 s2, 2, s0
	s_bitcmp1_b32 s1, 0
	s_cselect_b32 s0, s2, s0
	s_cmp_eq_u32 s0, 0
	s_cbranch_scc1 .Lmy_g2_passA
	s_cmp_eq_u32 s0, 1
	s_cbranch_scc1 .Lmy_g2_passB

; __global__ void __launch_bounds__(NWAVES * 64, 2) hybrid_fwd(Args A) {
;     ...
;             else if ((s == 2 && EN(3)) || (s == 3 && EN(4)) || (s == 4 && EN(5))) {
;                 const bool split = C.G >= 192; bool go = (s == 4); int k0 = split ? KSPLIT : 0, kl = D - k0, gg = C.G, cc = C.bid, mrows = M; size_t roff = 0;
;                 if (s == 2) { go = phase_mixers(A, C, l, rep ? DUP_UN : 7); k0 = 0; kl = KSPLIT; gg = C.G - 128; cc = C.bid - 128; mrows = MP; }
;                 if (s == 3) { phase_post(A, C, l, split ? 8 : 0); go = split && C.bid < 8 && !rep; k0 = 0; kl = KSPLIT; gg = 8; cc = C.bid; mrows = MS; roff = (size_t)MP * D; }
;                 if (go) { pg8::Gemm g{WS_PTR(const bf16, WS_XN) + roff + k0, WS_PTR(const bf16, WS_WOUTT) + (size_t)l * D * D + k0, mrows, D, kl, D}; pg8::StaticOrder S; S.init(mrows, D, gg, cc);
;                     const bool first = (l == 0) && (s != 4 || !split);
;                     float* Hout = ((rep && s == 4) ? WS_PTR(float, WS_U) : A.out) + roff;
;                     pg8::EpiResN E{Hout, first ? (s == 3 ? A.in[I_XS] : A.in[I_XP]) : Hout, first ? A.in[I_XS] - (size_t)MP * D : Hout, WS_PTR(bf16, WS_HB), WS_PTR(float, WS_SS) + (size_t)(l + 1) * M, s == 4 && !rep};
;                     pg8::gemm_phase<pg8::EpiResN, pg8::StaticOrder, G2_ALIGN, true>(C.lds, g, S, E); }
.Lmy_g2_passB:
	s_mov_b32 s11, 1
	s_mov_b64 s[40:41], 0x4000000
	s_mov_b32 s17, 8
	v_readlane_b32 s30, v253, 0
	v_readlane_b32 s3, v253, 19
	v_readlane_b32 s8, v253, 18
	s_mov_b32 s98, 0x8000
	v_writelane_b32 v255, s98, 63
	s_mov_b32 s98, 0
	v_writelane_b32 v255, s98, 62
	s_mov_b64 s[52:53], -1
	s_mov_b64 s[38:39], 0
	s_branch .LBB0_1189
.Lmy_g2_passA:
	s_movk_i32 s11, 0x50
	s_mov_b64 s[40:41], 0
	v_readlane_b32 s17, v253, 3
	v_readlane_b32 s30, v253, 0
	v_readlane_b32 s3, v253, 19
	v_readlane_b32 s8, v253, 18
	s_mov_b32 s98, 0
	v_writelane_b32 v255, s98, 63
	v_writelane_b32 v255, s98, 62
	s_mov_b64 s[52:53], -1
	s_mov_b64 s[38:39], 0
	s_branch .LBB0_1189
